# prompt attention: far chunks (constant bias) run as one fused 64-key step with rolling fragment reads and softmax VALU in the PV MFMA gaps; plus sample K loads up front
# speedup vs baseline: 1.0109x; 1.0109x over previous
.LBB0_81:
	s_cmp_lt_i32 s31, s26
	s_cselect_b64 s[0:1], -1, 0
	s_cmp_gt_i32 s31, s22
	s_cselect_b64 s[12:13], -1, 0
	s_or_b64 s[0:1], s[0:1], s[12:13]
	s_and_b64 vcc, exec, s[0:1]
	s_cbranch_vccnz .LBB0_88
	s_add_i32 s12, s31, 3
	s_cmp_le_i32 s12, s22
	s_cbranch_scc0 .Lpa0_near
	v_mad_u32_u24 v188, v149, s97, v176
	ds_read_b128 v[184:187], v188
	ds_read_b128 v[208:211], v188 offset:32
	ds_read_b128 v[212:215], v188 offset:64
	ds_read_b128 v[216:219], v188 offset:96
	ds_read_b128 v[224:227], v188 offset:128
	ds_read_b128 v[232:235], v188 offset:160
	ds_read_b128 v[236:239], v188 offset:192
	ds_read_b128 v[240:243], v188 offset:224
	s_waitcnt lgkmcnt(7)
	v_mfma_f32_32x32x16_bf16 v[66:81], v[184:187], v[102:105], 0
	ds_read_b128 v[184:187], v188 offset:8704
	s_waitcnt lgkmcnt(7)
	v_mfma_f32_32x32x16_bf16 v[66:81], v[208:211], v[106:109], v[66:81]
	ds_read_b128 v[208:211], v188 offset:8736
	s_waitcnt lgkmcnt(7)
	v_mfma_f32_32x32x16_bf16 v[66:81], v[212:215], v[114:117], v[66:81]
	ds_read_b128 v[212:215], v188 offset:8768
	s_waitcnt lgkmcnt(7)
	v_mfma_f32_32x32x16_bf16 v[66:81], v[216:219], v[118:121], v[66:81]
	ds_read_b128 v[216:219], v188 offset:8800
	s_waitcnt lgkmcnt(7)
	v_mfma_f32_32x32x16_bf16 v[66:81], v[224:227], v[122:125], v[66:81]
	ds_read_b128 v[224:227], v188 offset:8832
	s_waitcnt lgkmcnt(7)
	v_mfma_f32_32x32x16_bf16 v[66:81], v[232:235], v[126:129], v[66:81]
	ds_read_b128 v[232:235], v188 offset:8864
	s_waitcnt lgkmcnt(7)
	v_mfma_f32_32x32x16_bf16 v[66:81], v[236:239], v[130:133], v[66:81]
	ds_read_b128 v[236:239], v188 offset:8896
	s_waitcnt lgkmcnt(7)
	v_mfma_f32_32x32x16_bf16 v[66:81], v[240:243], v[134:137], v[66:81]
	ds_read_b128 v[240:243], v188 offset:8928
	s_waitcnt lgkmcnt(7)
	v_mfma_f32_32x32x16_bf16 v[192:207], v[184:187], v[102:105], 0
	ds_read_b128 v[184:187], v180 offset:17408
	s_waitcnt lgkmcnt(7)
	v_mfma_f32_32x32x16_bf16 v[192:207], v[208:211], v[106:109], v[192:207]
	ds_read_b128 v[208:211], v180 offset:22016
	s_waitcnt lgkmcnt(7)
	v_mfma_f32_32x32x16_bf16 v[192:207], v[212:215], v[114:117], v[192:207]
	ds_read_b128 v[212:215], v180 offset:26624
	s_waitcnt lgkmcnt(7)
	v_mfma_f32_32x32x16_bf16 v[192:207], v[216:219], v[118:121], v[192:207]
	ds_read_b128 v[216:219], v180 offset:31232
	s_waitcnt lgkmcnt(7)
	v_mfma_f32_32x32x16_bf16 v[192:207], v[224:227], v[122:125], v[192:207]
	ds_read_b128 v[224:227], v180 offset:17440
	v_max3_f32 v190, v66, v67, v68
	v_max3_f32 v223, v69, v70, v71
	s_waitcnt lgkmcnt(7)
	v_mfma_f32_32x32x16_bf16 v[192:207], v[232:235], v[126:129], v[192:207]
	ds_read_b128 v[232:235], v180 offset:22048
	v_max3_f32 v190, v190, v72, v73
	v_max3_f32 v223, v223, v74, v75
	s_waitcnt lgkmcnt(7)
	v_mfma_f32_32x32x16_bf16 v[192:207], v[236:239], v[130:133], v[192:207]
	ds_read_b128 v[236:239], v180 offset:26656
	v_max3_f32 v190, v190, v76, v77
	v_max3_f32 v223, v223, v78, v79
	s_waitcnt lgkmcnt(7)
	v_mfma_f32_32x32x16_bf16 v[192:207], v[240:243], v[134:137], v[192:207]
	ds_read_b128 v[240:243], v180 offset:31264
	v_max3_f32 v190, v190, v80, v81
	v_max_f32_e32 v190, v190, v223
	s_nop 7
	s_nop 3
	v_max3_f32 v223, v192, v193, v194
	v_max3_f32 v183, v195, v196, v197
	v_max3_f32 v223, v223, v198, v199
	v_max3_f32 v183, v183, v200, v201
	v_max3_f32 v223, v223, v202, v203
	v_max3_f32 v183, v183, v204, v205
	v_max3_f32 v223, v223, v206, v207
	v_max_f32_e32 v223, v223, v183
	v_max_f32_e32 v190, v190, v223
	v_add_f32_e32 v190, v157, v190
	v_mov_b32_e32 v223, v190
	s_nop 1
	v_permlane32_swap_b32_e32 v223, v190
	v_max_f32_e32 v190, v190, v223
	v_sub_f32_e32 v223, v190, v182
	v_cmp_lt_f32_e32 vcc, s60, v223
	s_cbranch_vccz .Lpf0_exp
	v_max_f32_e32 v190, v182, v190
	v_sub_f32_e32 v182, v182, v190
	v_exp_f32_e32 v182, v182
	s_nop 0
	v_mul_f32_e32 v153, v153, v182
	v_pk_mul_f32 v[64:65], v[64:65], v[182:183] op_sel_hi:[1,0]
	v_pk_mul_f32 v[62:63], v[62:63], v[182:183] op_sel_hi:[1,0]
	v_pk_mul_f32 v[60:61], v[60:61], v[182:183] op_sel_hi:[1,0]
	v_pk_mul_f32 v[58:59], v[58:59], v[182:183] op_sel_hi:[1,0]
	v_pk_mul_f32 v[56:57], v[56:57], v[182:183] op_sel_hi:[1,0]
	v_pk_mul_f32 v[54:55], v[54:55], v[182:183] op_sel_hi:[1,0]
	v_pk_mul_f32 v[52:53], v[52:53], v[182:183] op_sel_hi:[1,0]
	v_pk_mul_f32 v[50:51], v[50:51], v[182:183] op_sel_hi:[1,0]
	v_pk_mul_f32 v[48:49], v[48:49], v[182:183] op_sel_hi:[1,0]
	v_pk_mul_f32 v[46:47], v[46:47], v[182:183] op_sel_hi:[1,0]
	v_pk_mul_f32 v[44:45], v[44:45], v[182:183] op_sel_hi:[1,0]
	v_pk_mul_f32 v[42:43], v[42:43], v[182:183] op_sel_hi:[1,0]
	v_pk_mul_f32 v[40:41], v[40:41], v[182:183] op_sel_hi:[1,0]
	v_pk_mul_f32 v[38:39], v[38:39], v[182:183] op_sel_hi:[1,0]
	v_pk_mul_f32 v[36:37], v[36:37], v[182:183] op_sel_hi:[1,0]
	v_pk_mul_f32 v[34:35], v[34:35], v[182:183] op_sel_hi:[1,0]
	v_pk_mul_f32 v[32:33], v[32:33], v[182:183] op_sel_hi:[1,0]
	v_pk_mul_f32 v[30:31], v[30:31], v[182:183] op_sel_hi:[1,0]
	v_pk_mul_f32 v[28:29], v[28:29], v[182:183] op_sel_hi:[1,0]
	v_pk_mul_f32 v[26:27], v[26:27], v[182:183] op_sel_hi:[1,0]
	v_pk_mul_f32 v[24:25], v[24:25], v[182:183] op_sel_hi:[1,0]
	v_pk_mul_f32 v[22:23], v[22:23], v[182:183] op_sel_hi:[1,0]
	v_pk_mul_f32 v[20:21], v[20:21], v[182:183] op_sel_hi:[1,0]
	v_pk_mul_f32 v[18:19], v[18:19], v[182:183] op_sel_hi:[1,0]
	v_pk_mul_f32 v[16:17], v[16:17], v[182:183] op_sel_hi:[1,0]
	v_pk_mul_f32 v[14:15], v[14:15], v[182:183] op_sel_hi:[1,0]
	v_pk_mul_f32 v[12:13], v[12:13], v[182:183] op_sel_hi:[1,0]
	v_pk_mul_f32 v[10:11], v[10:11], v[182:183] op_sel_hi:[1,0]
	v_pk_mul_f32 v[8:9], v[8:9], v[182:183] op_sel_hi:[1,0]
	v_pk_mul_f32 v[6:7], v[6:7], v[182:183] op_sel_hi:[1,0]
	v_pk_mul_f32 v[4:5], v[4:5], v[182:183] op_sel_hi:[1,0]
	v_pk_mul_f32 v[2:3], v[2:3], v[182:183] op_sel_hi:[1,0]
	v_mov_b32_e32 v182, v190
.Lpf0_exp:
	v_sub_f32_e32 v188, v157, v182
	v_add_f32_e32 v66, v66, v188
	v_add_f32_e32 v67, v67, v188
	v_add_f32_e32 v68, v68, v188
	v_add_f32_e32 v69, v69, v188
	v_add_f32_e32 v70, v70, v188
	v_add_f32_e32 v71, v71, v188
	v_add_f32_e32 v72, v72, v188
	v_add_f32_e32 v73, v73, v188
	v_exp_f32_e32 v66, v66
	v_exp_f32_e32 v67, v67
	v_exp_f32_e32 v68, v68
	v_exp_f32_e32 v69, v69
	v_exp_f32_e32 v70, v70
	v_exp_f32_e32 v71, v71
	v_exp_f32_e32 v72, v72
	v_exp_f32_e32 v73, v73
	v_add_f32_e32 v190, v66, v67
	v_add_f32_e32 v223, v68, v69
	v_add_f32_e32 v190, v190, v223
	v_add_f32_e32 v223, v70, v71
	v_add_f32_e32 v190, v190, v223
	v_add_f32_e32 v223, v72, v73
	v_add_f32_e32 v190, v190, v223
	v_cvt_pk_bf16_f32 v66, v66, v67
	v_cvt_pk_bf16_f32 v67, v68, v69
	v_cvt_pk_bf16_f32 v68, v70, v71
	v_cvt_pk_bf16_f32 v69, v72, v73
	v_add_f32_e32 v153, v153, v190
	s_nop 0
	s_waitcnt lgkmcnt(7)
	v_mfma_f32_32x32x16_bf16 v[50:65], v[184:187], v[66:69], v[50:65]
	ds_read_b128 v[184:187], v180 offset:17472
	v_add_f32_e32 v74, v74, v188
	v_add_f32_e32 v75, v75, v188
	v_add_f32_e32 v76, v76, v188
	v_add_f32_e32 v77, v77, v188
	v_add_f32_e32 v78, v78, v188
	v_add_f32_e32 v79, v79, v188
	v_add_f32_e32 v80, v80, v188
	s_waitcnt lgkmcnt(7)
	v_mfma_f32_32x32x16_bf16 v[34:49], v[208:211], v[66:69], v[34:49]
	ds_read_b128 v[208:211], v180 offset:22080
	v_add_f32_e32 v81, v81, v188
	v_exp_f32_e32 v74, v74
	v_exp_f32_e32 v75, v75
	v_exp_f32_e32 v76, v76
	v_exp_f32_e32 v77, v77
	v_exp_f32_e32 v78, v78
	v_exp_f32_e32 v79, v79
	s_waitcnt lgkmcnt(7)
	v_mfma_f32_32x32x16_bf16 v[18:33], v[212:215], v[66:69], v[18:33]
	ds_read_b128 v[212:215], v180 offset:26688
	v_exp_f32_e32 v80, v80
	v_exp_f32_e32 v81, v81
	v_add_f32_e32 v190, v74, v75
	v_add_f32_e32 v223, v76, v77
	v_add_f32_e32 v190, v190, v223
	v_add_f32_e32 v223, v78, v79
	v_add_f32_e32 v190, v190, v223
	s_waitcnt lgkmcnt(7)
	v_mfma_f32_32x32x16_bf16 v[2:17], v[216:219], v[66:69], v[2:17]
	ds_read_b128 v[216:219], v180 offset:31296
	v_add_f32_e32 v223, v80, v81
	v_add_f32_e32 v190, v190, v223
	v_cvt_pk_bf16_f32 v70, v74, v75
	v_cvt_pk_bf16_f32 v71, v76, v77
	v_cvt_pk_bf16_f32 v72, v78, v79
	v_cvt_pk_bf16_f32 v73, v80, v81
	v_add_f32_e32 v153, v153, v190
	s_waitcnt lgkmcnt(7)
	v_mfma_f32_32x32x16_bf16 v[50:65], v[224:227], v[70:73], v[50:65]
	ds_read_b128 v[224:227], v180 offset:17504
	v_add_f32_e32 v192, v192, v188
	v_add_f32_e32 v193, v193, v188
	v_add_f32_e32 v194, v194, v188
	v_add_f32_e32 v195, v195, v188
	v_add_f32_e32 v196, v196, v188
	v_add_f32_e32 v197, v197, v188
	v_add_f32_e32 v198, v198, v188
	s_waitcnt lgkmcnt(7)
	v_mfma_f32_32x32x16_bf16 v[34:49], v[232:235], v[70:73], v[34:49]
	ds_read_b128 v[232:235], v180 offset:22112
	v_add_f32_e32 v199, v199, v188
	v_exp_f32_e32 v192, v192
	v_exp_f32_e32 v193, v193
	v_exp_f32_e32 v194, v194
	v_exp_f32_e32 v195, v195
	v_exp_f32_e32 v196, v196
	v_exp_f32_e32 v197, v197
	s_waitcnt lgkmcnt(7)
	v_mfma_f32_32x32x16_bf16 v[18:33], v[236:239], v[70:73], v[18:33]
	ds_read_b128 v[236:239], v180 offset:26720
	v_exp_f32_e32 v198, v198
	v_exp_f32_e32 v199, v199
	v_add_f32_e32 v190, v192, v193
	v_add_f32_e32 v223, v194, v195
	v_add_f32_e32 v190, v190, v223
	v_add_f32_e32 v223, v196, v197
	v_add_f32_e32 v190, v190, v223
	s_waitcnt lgkmcnt(7)
	v_mfma_f32_32x32x16_bf16 v[2:17], v[240:243], v[70:73], v[2:17]
	ds_read_b128 v[240:243], v180 offset:31328
	v_add_f32_e32 v223, v198, v199
	v_add_f32_e32 v190, v190, v223
	v_cvt_pk_bf16_f32 v192, v192, v193
	v_cvt_pk_bf16_f32 v193, v194, v195
	v_cvt_pk_bf16_f32 v194, v196, v197
	v_cvt_pk_bf16_f32 v195, v198, v199
	v_add_f32_e32 v153, v153, v190
	s_waitcnt lgkmcnt(7)
	v_mfma_f32_32x32x16_bf16 v[50:65], v[184:187], v[192:195], v[50:65]
	v_add_f32_e32 v200, v200, v188
	v_add_f32_e32 v201, v201, v188
	v_add_f32_e32 v202, v202, v188
	v_add_f32_e32 v203, v203, v188
	v_add_f32_e32 v204, v204, v188
	v_add_f32_e32 v205, v205, v188
	v_add_f32_e32 v206, v206, v188
	s_waitcnt lgkmcnt(6)
	v_mfma_f32_32x32x16_bf16 v[34:49], v[208:211], v[192:195], v[34:49]
	v_add_f32_e32 v207, v207, v188
	v_exp_f32_e32 v200, v200
	v_exp_f32_e32 v201, v201
	v_exp_f32_e32 v202, v202
	v_exp_f32_e32 v203, v203
	v_exp_f32_e32 v204, v204
	v_exp_f32_e32 v205, v205
	s_waitcnt lgkmcnt(5)
	v_mfma_f32_32x32x16_bf16 v[18:33], v[212:215], v[192:195], v[18:33]
	v_exp_f32_e32 v206, v206
	v_exp_f32_e32 v207, v207
	v_add_f32_e32 v190, v200, v201
	v_add_f32_e32 v223, v202, v203
	v_add_f32_e32 v190, v190, v223
	v_add_f32_e32 v223, v204, v205
	v_add_f32_e32 v190, v190, v223
	s_waitcnt lgkmcnt(4)
	v_mfma_f32_32x32x16_bf16 v[2:17], v[216:219], v[192:195], v[2:17]
	v_add_f32_e32 v223, v206, v207
	v_add_f32_e32 v190, v190, v223
	v_cvt_pk_bf16_f32 v196, v200, v201
	v_cvt_pk_bf16_f32 v197, v202, v203
	v_cvt_pk_bf16_f32 v198, v204, v205
	v_cvt_pk_bf16_f32 v199, v206, v207
	v_add_f32_e32 v153, v153, v190
	s_waitcnt lgkmcnt(3)
	v_mfma_f32_32x32x16_bf16 v[50:65], v[224:227], v[196:199], v[50:65]
	s_waitcnt lgkmcnt(2)
	v_mfma_f32_32x32x16_bf16 v[34:49], v[232:235], v[196:199], v[34:49]
	s_waitcnt lgkmcnt(1)
	v_mfma_f32_32x32x16_bf16 v[18:33], v[236:239], v[196:199], v[18:33]
	s_waitcnt lgkmcnt(0)
	v_mfma_f32_32x32x16_bf16 v[2:17], v[240:243], v[196:199], v[2:17]
	s_branch .LBB0_88
.Lpa0_near:
	s_lshl_b32 s0, s31, 6
	v_sub_u32_e32 v183, s0, v155
	s_mov_b32 s33, 0

.LBB0_90:
	s_or_b32 s0, s31, 1
	s_cmp_lt_i32 s0, s26
	s_cselect_b64 s[12:13], -1, 0
	s_cmp_ge_i32 s31, s22
	s_cselect_b64 s[14:15], -1, 0
	s_or_b64 s[12:13], s[14:15], s[12:13]
	s_and_b64 vcc, exec, s[12:13]
	s_cbranch_vccnz .LBB0_97
	s_or_b32 s12, s31, 1
	s_add_i32 s12, s12, 3
	s_cmp_le_i32 s12, s22
	s_cbranch_scc0 .Lpa1_near
	v_mad_u32_u24 v188, v149, s97, v176
	v_add_u32_e32 v244, 0x8c00, v180
	ds_read_b128 v[184:187], v188 offset:35840
	ds_read_b128 v[208:211], v188 offset:35872
	ds_read_b128 v[212:215], v188 offset:35904
	ds_read_b128 v[216:219], v188 offset:35936
	ds_read_b128 v[224:227], v188 offset:35968
	ds_read_b128 v[232:235], v188 offset:36000
	ds_read_b128 v[236:239], v188 offset:36032
	ds_read_b128 v[240:243], v188 offset:36064
	s_waitcnt lgkmcnt(7)
	v_mfma_f32_32x32x16_bf16 v[66:81], v[184:187], v[102:105], 0
	ds_read_b128 v[184:187], v188 offset:44544
	s_waitcnt lgkmcnt(7)
	v_mfma_f32_32x32x16_bf16 v[66:81], v[208:211], v[106:109], v[66:81]
	ds_read_b128 v[208:211], v188 offset:44576
	s_waitcnt lgkmcnt(7)
	v_mfma_f32_32x32x16_bf16 v[66:81], v[212:215], v[114:117], v[66:81]
	ds_read_b128 v[212:215], v188 offset:44608
	s_waitcnt lgkmcnt(7)
	v_mfma_f32_32x32x16_bf16 v[66:81], v[216:219], v[118:121], v[66:81]
	ds_read_b128 v[216:219], v188 offset:44640
	s_waitcnt lgkmcnt(7)
	v_mfma_f32_32x32x16_bf16 v[66:81], v[224:227], v[122:125], v[66:81]
	ds_read_b128 v[224:227], v188 offset:44672
	s_waitcnt lgkmcnt(7)
	v_mfma_f32_32x32x16_bf16 v[66:81], v[232:235], v[126:129], v[66:81]
	ds_read_b128 v[232:235], v188 offset:44704
	s_waitcnt lgkmcnt(7)
	v_mfma_f32_32x32x16_bf16 v[66:81], v[236:239], v[130:133], v[66:81]
	ds_read_b128 v[236:239], v188 offset:44736
	s_waitcnt lgkmcnt(7)
	v_mfma_f32_32x32x16_bf16 v[66:81], v[240:243], v[134:137], v[66:81]
	ds_read_b128 v[240:243], v188 offset:44768
	s_waitcnt lgkmcnt(7)
	v_mfma_f32_32x32x16_bf16 v[192:207], v[184:187], v[102:105], 0
	ds_read_b128 v[184:187], v244 offset:17408
	s_waitcnt lgkmcnt(7)
	v_mfma_f32_32x32x16_bf16 v[192:207], v[208:211], v[106:109], v[192:207]
	ds_read_b128 v[208:211], v244 offset:22016
	s_waitcnt lgkmcnt(7)
	v_mfma_f32_32x32x16_bf16 v[192:207], v[212:215], v[114:117], v[192:207]
	ds_read_b128 v[212:215], v244 offset:26624
	s_waitcnt lgkmcnt(7)
	v_mfma_f32_32x32x16_bf16 v[192:207], v[216:219], v[118:121], v[192:207]
	ds_read_b128 v[216:219], v244 offset:31232
	s_waitcnt lgkmcnt(7)
	v_mfma_f32_32x32x16_bf16 v[192:207], v[224:227], v[122:125], v[192:207]
	ds_read_b128 v[224:227], v244 offset:17440
	v_max3_f32 v190, v66, v67, v68
	v_max3_f32 v223, v69, v70, v71
	s_waitcnt lgkmcnt(7)
	v_mfma_f32_32x32x16_bf16 v[192:207], v[232:235], v[126:129], v[192:207]
	ds_read_b128 v[232:235], v244 offset:22048
	v_max3_f32 v190, v190, v72, v73
	v_max3_f32 v223, v223, v74, v75
	s_waitcnt lgkmcnt(7)
	v_mfma_f32_32x32x16_bf16 v[192:207], v[236:239], v[130:133], v[192:207]
	ds_read_b128 v[236:239], v244 offset:26656
	v_max3_f32 v190, v190, v76, v77
	v_max3_f32 v223, v223, v78, v79
	s_waitcnt lgkmcnt(7)
	v_mfma_f32_32x32x16_bf16 v[192:207], v[240:243], v[134:137], v[192:207]
	ds_read_b128 v[240:243], v244 offset:31264
	v_max3_f32 v190, v190, v80, v81
	v_max_f32_e32 v190, v190, v223
	s_nop 7
	s_nop 3
	v_max3_f32 v223, v192, v193, v194
	v_max3_f32 v183, v195, v196, v197
	v_max3_f32 v223, v223, v198, v199
	v_max3_f32 v183, v183, v200, v201
	v_max3_f32 v223, v223, v202, v203
	v_max3_f32 v183, v183, v204, v205
	v_max3_f32 v223, v223, v206, v207
	v_max_f32_e32 v223, v223, v183
	v_max_f32_e32 v190, v190, v223
	v_add_f32_e32 v190, v157, v190
	v_mov_b32_e32 v223, v190
	s_nop 1
	v_permlane32_swap_b32_e32 v223, v190
	v_max_f32_e32 v190, v190, v223
	v_sub_f32_e32 v223, v190, v182
	v_cmp_lt_f32_e32 vcc, s60, v223
	s_cbranch_vccz .Lpf1_exp
	v_max_f32_e32 v190, v182, v190
	v_sub_f32_e32 v182, v182, v190
	v_exp_f32_e32 v182, v182
	s_nop 0
	v_mul_f32_e32 v153, v153, v182
	v_pk_mul_f32 v[64:65], v[64:65], v[182:183] op_sel_hi:[1,0]
	v_pk_mul_f32 v[62:63], v[62:63], v[182:183] op_sel_hi:[1,0]
	v_pk_mul_f32 v[60:61], v[60:61], v[182:183] op_sel_hi:[1,0]
	v_pk_mul_f32 v[58:59], v[58:59], v[182:183] op_sel_hi:[1,0]
	v_pk_mul_f32 v[56:57], v[56:57], v[182:183] op_sel_hi:[1,0]
	v_pk_mul_f32 v[54:55], v[54:55], v[182:183] op_sel_hi:[1,0]
	v_pk_mul_f32 v[52:53], v[52:53], v[182:183] op_sel_hi:[1,0]
	v_pk_mul_f32 v[50:51], v[50:51], v[182:183] op_sel_hi:[1,0]
	v_pk_mul_f32 v[48:49], v[48:49], v[182:183] op_sel_hi:[1,0]
	v_pk_mul_f32 v[46:47], v[46:47], v[182:183] op_sel_hi:[1,0]
	v_pk_mul_f32 v[44:45], v[44:45], v[182:183] op_sel_hi:[1,0]
	v_pk_mul_f32 v[42:43], v[42:43], v[182:183] op_sel_hi:[1,0]
	v_pk_mul_f32 v[40:41], v[40:41], v[182:183] op_sel_hi:[1,0]
	v_pk_mul_f32 v[38:39], v[38:39], v[182:183] op_sel_hi:[1,0]
	v_pk_mul_f32 v[36:37], v[36:37], v[182:183] op_sel_hi:[1,0]
	v_pk_mul_f32 v[34:35], v[34:35], v[182:183] op_sel_hi:[1,0]
	v_pk_mul_f32 v[32:33], v[32:33], v[182:183] op_sel_hi:[1,0]
	v_pk_mul_f32 v[30:31], v[30:31], v[182:183] op_sel_hi:[1,0]
	v_pk_mul_f32 v[28:29], v[28:29], v[182:183] op_sel_hi:[1,0]
	v_pk_mul_f32 v[26:27], v[26:27], v[182:183] op_sel_hi:[1,0]
	v_pk_mul_f32 v[24:25], v[24:25], v[182:183] op_sel_hi:[1,0]
	v_pk_mul_f32 v[22:23], v[22:23], v[182:183] op_sel_hi:[1,0]
	v_pk_mul_f32 v[20:21], v[20:21], v[182:183] op_sel_hi:[1,0]
	v_pk_mul_f32 v[18:19], v[18:19], v[182:183] op_sel_hi:[1,0]
	v_pk_mul_f32 v[16:17], v[16:17], v[182:183] op_sel_hi:[1,0]
	v_pk_mul_f32 v[14:15], v[14:15], v[182:183] op_sel_hi:[1,0]
	v_pk_mul_f32 v[12:13], v[12:13], v[182:183] op_sel_hi:[1,0]
	v_pk_mul_f32 v[10:11], v[10:11], v[182:183] op_sel_hi:[1,0]
	v_pk_mul_f32 v[8:9], v[8:9], v[182:183] op_sel_hi:[1,0]
	v_pk_mul_f32 v[6:7], v[6:7], v[182:183] op_sel_hi:[1,0]
	v_pk_mul_f32 v[4:5], v[4:5], v[182:183] op_sel_hi:[1,0]
	v_pk_mul_f32 v[2:3], v[2:3], v[182:183] op_sel_hi:[1,0]
	v_mov_b32_e32 v182, v190
.Lpf1_exp:
	v_sub_f32_e32 v188, v157, v182
	v_add_f32_e32 v66, v66, v188
	v_add_f32_e32 v67, v67, v188
	v_add_f32_e32 v68, v68, v188
	v_add_f32_e32 v69, v69, v188
	v_add_f32_e32 v70, v70, v188
	v_add_f32_e32 v71, v71, v188
	v_add_f32_e32 v72, v72, v188
	v_add_f32_e32 v73, v73, v188
	v_exp_f32_e32 v66, v66
	v_exp_f32_e32 v67, v67
	v_exp_f32_e32 v68, v68
	v_exp_f32_e32 v69, v69
	v_exp_f32_e32 v70, v70
	v_exp_f32_e32 v71, v71
	v_exp_f32_e32 v72, v72
	v_exp_f32_e32 v73, v73
	v_add_f32_e32 v190, v66, v67
	v_add_f32_e32 v223, v68, v69
	v_add_f32_e32 v190, v190, v223
	v_add_f32_e32 v223, v70, v71
	v_add_f32_e32 v190, v190, v223
	v_add_f32_e32 v223, v72, v73
	v_add_f32_e32 v190, v190, v223
	v_cvt_pk_bf16_f32 v66, v66, v67
	v_cvt_pk_bf16_f32 v67, v68, v69
	v_cvt_pk_bf16_f32 v68, v70, v71
	v_cvt_pk_bf16_f32 v69, v72, v73
	v_add_f32_e32 v153, v153, v190
	s_nop 0
	s_waitcnt lgkmcnt(7)
	v_mfma_f32_32x32x16_bf16 v[50:65], v[184:187], v[66:69], v[50:65]
	ds_read_b128 v[184:187], v244 offset:17472
	v_add_f32_e32 v74, v74, v188
	v_add_f32_e32 v75, v75, v188
	v_add_f32_e32 v76, v76, v188
	v_add_f32_e32 v77, v77, v188
	v_add_f32_e32 v78, v78, v188
	v_add_f32_e32 v79, v79, v188
	v_add_f32_e32 v80, v80, v188
	s_waitcnt lgkmcnt(7)
	v_mfma_f32_32x32x16_bf16 v[34:49], v[208:211], v[66:69], v[34:49]
	ds_read_b128 v[208:211], v244 offset:22080
	v_add_f32_e32 v81, v81, v188
	v_exp_f32_e32 v74, v74
	v_exp_f32_e32 v75, v75
	v_exp_f32_e32 v76, v76
	v_exp_f32_e32 v77, v77
	v_exp_f32_e32 v78, v78
	v_exp_f32_e32 v79, v79
	s_waitcnt lgkmcnt(7)
	v_mfma_f32_32x32x16_bf16 v[18:33], v[212:215], v[66:69], v[18:33]
	ds_read_b128 v[212:215], v244 offset:26688
	v_exp_f32_e32 v80, v80
	v_exp_f32_e32 v81, v81
	v_add_f32_e32 v190, v74, v75
	v_add_f32_e32 v223, v76, v77
	v_add_f32_e32 v190, v190, v223
	v_add_f32_e32 v223, v78, v79
	v_add_f32_e32 v190, v190, v223
	s_waitcnt lgkmcnt(7)
	v_mfma_f32_32x32x16_bf16 v[2:17], v[216:219], v[66:69], v[2:17]
	ds_read_b128 v[216:219], v244 offset:31296
	v_add_f32_e32 v223, v80, v81
	v_add_f32_e32 v190, v190, v223
	v_cvt_pk_bf16_f32 v70, v74, v75
	v_cvt_pk_bf16_f32 v71, v76, v77
	v_cvt_pk_bf16_f32 v72, v78, v79
	v_cvt_pk_bf16_f32 v73, v80, v81
	v_add_f32_e32 v153, v153, v190
	s_waitcnt lgkmcnt(7)
	v_mfma_f32_32x32x16_bf16 v[50:65], v[224:227], v[70:73], v[50:65]
	ds_read_b128 v[224:227], v244 offset:17504
	v_add_f32_e32 v192, v192, v188
	v_add_f32_e32 v193, v193, v188
	v_add_f32_e32 v194, v194, v188
	v_add_f32_e32 v195, v195, v188
	v_add_f32_e32 v196, v196, v188
	v_add_f32_e32 v197, v197, v188
	v_add_f32_e32 v198, v198, v188
	s_waitcnt lgkmcnt(7)
	v_mfma_f32_32x32x16_bf16 v[34:49], v[232:235], v[70:73], v[34:49]
	ds_read_b128 v[232:235], v244 offset:22112
	v_add_f32_e32 v199, v199, v188
	v_exp_f32_e32 v192, v192
	v_exp_f32_e32 v193, v193
	v_exp_f32_e32 v194, v194
	v_exp_f32_e32 v195, v195
	v_exp_f32_e32 v196, v196
	v_exp_f32_e32 v197, v197
	s_waitcnt lgkmcnt(7)
	v_mfma_f32_32x32x16_bf16 v[18:33], v[236:239], v[70:73], v[18:33]
	ds_read_b128 v[236:239], v244 offset:26720
	v_exp_f32_e32 v198, v198
	v_exp_f32_e32 v199, v199
	v_add_f32_e32 v190, v192, v193
	v_add_f32_e32 v223, v194, v195
	v_add_f32_e32 v190, v190, v223
	v_add_f32_e32 v223, v196, v197
	v_add_f32_e32 v190, v190, v223
	s_waitcnt lgkmcnt(7)
	v_mfma_f32_32x32x16_bf16 v[2:17], v[240:243], v[70:73], v[2:17]
	ds_read_b128 v[240:243], v244 offset:31328
	v_add_f32_e32 v223, v198, v199
	v_add_f32_e32 v190, v190, v223
	v_cvt_pk_bf16_f32 v192, v192, v193
	v_cvt_pk_bf16_f32 v193, v194, v195
	v_cvt_pk_bf16_f32 v194, v196, v197
	v_cvt_pk_bf16_f32 v195, v198, v199
	v_add_f32_e32 v153, v153, v190
	s_waitcnt lgkmcnt(7)
	v_mfma_f32_32x32x16_bf16 v[50:65], v[184:187], v[192:195], v[50:65]
	v_add_f32_e32 v200, v200, v188
	v_add_f32_e32 v201, v201, v188
	v_add_f32_e32 v202, v202, v188
	v_add_f32_e32 v203, v203, v188
	v_add_f32_e32 v204, v204, v188
	v_add_f32_e32 v205, v205, v188
	v_add_f32_e32 v206, v206, v188
	s_waitcnt lgkmcnt(6)
	v_mfma_f32_32x32x16_bf16 v[34:49], v[208:211], v[192:195], v[34:49]
	v_add_f32_e32 v207, v207, v188
	v_exp_f32_e32 v200, v200
	v_exp_f32_e32 v201, v201
	v_exp_f32_e32 v202, v202
	v_exp_f32_e32 v203, v203
	v_exp_f32_e32 v204, v204
	v_exp_f32_e32 v205, v205
	s_waitcnt lgkmcnt(5)
	v_mfma_f32_32x32x16_bf16 v[18:33], v[212:215], v[192:195], v[18:33]
	v_exp_f32_e32 v206, v206
	v_exp_f32_e32 v207, v207
	v_add_f32_e32 v190, v200, v201
	v_add_f32_e32 v223, v202, v203
	v_add_f32_e32 v190, v190, v223
	v_add_f32_e32 v223, v204, v205
	v_add_f32_e32 v190, v190, v223
	s_waitcnt lgkmcnt(4)
	v_mfma_f32_32x32x16_bf16 v[2:17], v[216:219], v[192:195], v[2:17]
	v_add_f32_e32 v223, v206, v207
	v_add_f32_e32 v190, v190, v223
	v_cvt_pk_bf16_f32 v196, v200, v201
	v_cvt_pk_bf16_f32 v197, v202, v203
	v_cvt_pk_bf16_f32 v198, v204, v205
	v_cvt_pk_bf16_f32 v199, v206, v207
	v_add_f32_e32 v153, v153, v190
	s_waitcnt lgkmcnt(3)
	v_mfma_f32_32x32x16_bf16 v[50:65], v[224:227], v[196:199], v[50:65]
	s_waitcnt lgkmcnt(2)
	v_mfma_f32_32x32x16_bf16 v[34:49], v[232:235], v[196:199], v[34:49]
	s_waitcnt lgkmcnt(1)
	v_mfma_f32_32x32x16_bf16 v[18:33], v[236:239], v[196:199], v[18:33]
	s_waitcnt lgkmcnt(0)
	v_mfma_f32_32x32x16_bf16 v[2:17], v[240:243], v[196:199], v[2:17]
	s_branch .LBB0_97
.Lpa1_near:
	s_lshl_b32 s0, s0, 6
	v_sub_u32_e32 v183, s0, v155
	s_mov_b32 s33, 0
